# v005 + half of the workgroups (those with one tile fewer) start the in-proj GEMM phase ~11us later so store bursts of the two halves do not collide
# speedup vs baseline: 1.0377x; 1.0106x over previous
.LBB0_207:
	s_or_b64 exec, exec, s[0:1]
	v_readlane_b32 s0, v247, 0
	v_readlane_b32 s1, v247, 1
	s_load_dwordx4 s[68:71], s[0:1], 0xc0
	v_readfirstlane_b32 s0, v184
	s_lshr_b32 s1, s0, 6
	v_bfe_u32 v2, v184, 5, 1
	v_lshrrev_b32_e32 v3, 1, v184
	s_waitcnt lgkmcnt(0)
	s_add_u32 s3, s70, 0x175100
	v_mov_b32_e32 v9, 0x3f2d8066
	v_mov_b32_e32 v10, 0x3fc45f30
	v_cmp_gt_u32_e64 s[44:45], 32, v207
	s_addc_u32 s33, s71, 0
	v_bfe_u32 v4, v184, 1, 3
	v_bitop3_b32 v3, v2, v3, 7 bitop3:0x78
	v_cndmask_b32_e64 v71, v9, v10, s[44:45]
	v_mov_b32_e32 v9, 0x912545c4
	v_mov_b32_e32 v10, 0x6dc9c883
	s_add_u32 s50, s70, 0x2b75100
	s_mulk_i32 s1, 0x3000
	v_and_b32_e32 v208, 7, v184
	v_lshlrev_b32_e32 v211, 4, v3
	v_bitop3_b32 v3, v2, v4, 2 bitop3:0x36
	v_mov_b32_e32 v67, 0
	v_cndmask_b32_e64 v70, v9, v10, s[44:45]
	v_mov_b32_e32 v9, 0x3f06e254
	v_mov_b32_e32 v10, 0x3f9f9ac0
	s_addc_u32 s51, s71, 0
	s_add_i32 s8, s1, 0x100
	s_and_b32 s6, s86, 7
	v_lshlrev_b32_e32 v212, 4, v3
	v_bitop3_b32 v3, v2, v4, 4 bitop3:0x36
	v_lshlrev_b32_e32 v186, 4, v208
	v_mov_b32_e32 v187, v67
	v_cndmask_b32_e64 v73, v9, v10, s[44:45]
	v_mov_b32_e32 v9, 0x3cfe9378
	v_mov_b32_e32 v10, 0x19d195e7
	s_cmp_lg_u32 s6, 0
	v_lshlrev_b32_e32 v213, 4, v3
	v_bitop3_b32 v3, v2, v4, 6 bitop3:0x36
	v_lshl_add_u64 v[4:5], s[70:71], 0, v[186:187]
	s_mov_b64 s[6:7], 0x4c75100
	v_cndmask_b32_e64 v72, v9, v10, s[44:45]
	v_mov_b32_e32 v9, 0x3ee1c040
	v_mov_b32_e32 v10, 0x3f7883ec
	s_cselect_b64 s[12:13], -1, 0
	s_and_b32 s56, s0, 64
	s_lshr_b32 s0, s0, 1
	v_lshl_add_u64 v[68:69], v[4:5], 0, s[6:7]
	v_and_b32_e32 v4, 15, v184
	v_cndmask_b32_e64 v75, v9, v10, s[44:45]
	v_mov_b32_e32 v9, 0xc4a3df88
	v_mov_b32_e32 v10, 0xe5870a9
	v_and_b32_e32 v189, 31, v184
	v_bfe_u32 v209, v184, 4, 2
	v_bfe_u32 v210, v184, 3, 3
	v_lshlrev_b32_e32 v214, 4, v3
	s_and_b32 s57, s0, 0x7fffffc0
	s_movk_i32 s0, 0x110
	v_mov_b32_e32 v3, s8
	v_lshlrev_b32_e32 v187, 4, v4
	v_cndmask_b32_e64 v74, v9, v10, s[44:45]
	v_mov_b32_e32 v9, 0x3ebb89df
	v_mov_b32_e32 v10, 0x3f53042d
	v_mad_u32_u24 v3, v189, s0, v3
	v_lshlrev_b32_e32 v6, 4, v2
	v_lshlrev_b32_e32 v2, 2, v2
	v_lshl_add_u32 v7, v208, 5, s8
	v_add_u32_e32 v5, s8, v187
	v_lshlrev_b32_e32 v188, 2, v4
	v_mul_u32_u24_e32 v4, 0x110, v210
	v_mul_u32_u24_e32 v8, 0x110, v209
	v_cndmask_b32_e64 v77, v9, v10, s[44:45]
	v_mov_b32_e32 v9, 0x4317ad85
	v_mov_b32_e32 v10, 0x185ebce3
	s_mov_b32 s1, 0
	s_ashr_i32 s52, s2, 3
	s_ashr_i32 s53, s86, 3
	s_bfe_u32 s54, s2, 0x10002
	s_and_b32 s55, s40, 24
	v_or_b32_e32 v90, 4, v209
	v_or_b32_e32 v91, 8, v209
	v_or_b32_e32 v92, 12, v209
	v_or_b32_e32 v93, 16, v209
	v_or_b32_e32 v94, 20, v209
	v_or_b32_e32 v95, 24, v209
	v_or_b32_e32 v96, 28, v209
	v_or_b32_e32 v97, 8, v210
	v_or_b32_e32 v98, 16, v210
	v_or_b32_e32 v99, 24, v210
	v_cndmask_b32_e64 v76, v9, v10, s[44:45]
	s_mov_b64 s[14:15], 0x20000
	s_mov_b64 s[16:17], 0x40000
	s_mov_b64 s[18:19], 0x60000
	s_mov_b64 s[20:21], 0x175180
	s_mov_b64 s[22:23], 0x195180
	s_mov_b64 s[24:25], 0x2b75180
	s_mov_b64 s[26:27], 0x2b95180
	s_mov_b64 s[28:29], 0x2bb5180
	s_mov_b64 s[30:31], 0x2bd5180
	s_movk_i32 s58, 0xa8
	s_mov_b32 s59, 0x2880000
	s_mov_b32 s60, 0x2080000
	s_mov_b32 s61, 0x1880000
	s_mov_b32 s62, 0x1080000
	v_mov_b32_e32 v100, 0x358637bd
	s_mov_b32 s63, 0x800000
	v_lshlrev_b32_e32 v66, 2, v2
	v_mbcnt_hi_u32_b32 v215, -1, v185
	v_add_u32_e32 v101, v3, v6
	v_add_u32_e32 v102, v5, v8
	v_mov_b32_e32 v103, 0x3e38aa3b
	v_add_u32_e32 v104, v7, v4
	v_mov_b32_e32 v105, 0x400
	s_mov_b32 s64, 0
	s_barrier
	s_cmp_lt_u32 s2, 0x80
	s_cbranch_scc1 .Lg1_nodelay
	s_movk_i32 s72, 3
.Lg1_delay:
	s_sleep 127
	s_add_i32 s72, s72, -1
	s_cmp_lg_u32 s72, 0
	s_cbranch_scc1 .Lg1_delay
.Lg1_nodelay:
	s_branch .LBB0_210
.LBB0_208:
	ds_read_b128 v[2:5], v104
	ds_read_b128 v[6:9], v104 offset:16
	v_mov_b32_e32 v37, v36
	v_or_b32_e32 v10, s40, v210
	v_ashrrev_i32_e32 v11, 31, v10
	s_waitcnt lgkmcnt(1)
	v_pk_mul_f32 v[2:3], v[36:37], v[2:3]
	v_pk_mul_f32 v[4:5], v[36:37], v[4:5]
	s_waitcnt lgkmcnt(0)
	v_pk_mul_f32 v[6:7], v[36:37], v[6:7]
	v_pk_mul_f32 v[8:9], v[36:37], v[8:9]
	v_cvt_pk_bf16_f32 v2, v2, v3
	v_cvt_pk_bf16_f32 v3, v4, v5
	v_cvt_pk_bf16_f32 v4, v6, v7
	v_cvt_pk_bf16_f32 v5, v8, v9
	ds_read_b128 v[6:9], v104 offset:2176
	v_lshlrev_b64 v[14:15], 13, v[10:11]
	ds_read_b128 v[10:13], v104 offset:2192
	v_lshl_add_u64 v[14:15], v[34:35], 0, v[14:15]
	global_store_dwordx4 v[14:15], v[2:5], off
	s_mov_b64 s[6:7], -1
	s_waitcnt lgkmcnt(1)
	v_pk_mul_f32 v[2:3], v[36:37], v[6:7]
	s_waitcnt lgkmcnt(0)
	v_pk_mul_f32 v[6:7], v[36:37], v[10:11]
	v_or_b32_e32 v10, s40, v97
	v_pk_mul_f32 v[4:5], v[36:37], v[8:9]
	v_pk_mul_f32 v[8:9], v[36:37], v[12:13]
	v_ashrrev_i32_e32 v11, 31, v10
	v_cvt_pk_bf16_f32 v2, v2, v3
	v_cvt_pk_bf16_f32 v3, v4, v5
	v_cvt_pk_bf16_f32 v4, v6, v7
	v_cvt_pk_bf16_f32 v5, v8, v9
	ds_read_b128 v[6:9], v104 offset:4352
	v_lshlrev_b64 v[14:15], 13, v[10:11]
	ds_read_b128 v[10:13], v104 offset:4368
	v_lshl_add_u64 v[14:15], v[34:35], 0, v[14:15]
	global_store_dwordx4 v[14:15], v[2:5], off
	s_waitcnt lgkmcnt(1)
	s_nop 0
	v_pk_mul_f32 v[2:3], v[36:37], v[6:7]
	s_waitcnt lgkmcnt(0)
	v_pk_mul_f32 v[6:7], v[36:37], v[10:11]
	v_or_b32_e32 v10, s40, v98
	v_pk_mul_f32 v[4:5], v[36:37], v[8:9]
	v_pk_mul_f32 v[8:9], v[36:37], v[12:13]
	v_ashrrev_i32_e32 v11, 31, v10
	v_cvt_pk_bf16_f32 v2, v2, v3
	v_cvt_pk_bf16_f32 v3, v4, v5
	v_cvt_pk_bf16_f32 v4, v6, v7
	v_cvt_pk_bf16_f32 v5, v8, v9
	ds_read_b128 v[6:9], v104 offset:6528
	v_lshlrev_b64 v[14:15], 13, v[10:11]
	ds_read_b128 v[10:13], v104 offset:6544
	v_lshl_add_u64 v[14:15], v[34:35], 0, v[14:15]
	global_store_dwordx4 v[14:15], v[2:5], off
	s_waitcnt lgkmcnt(1)
	s_nop 0
	v_pk_mul_f32 v[2:3], v[36:37], v[6:7]
	v_pk_mul_f32 v[4:5], v[36:37], v[8:9]
	s_waitcnt lgkmcnt(0)
	v_pk_mul_f32 v[6:7], v[36:37], v[10:11]
	v_cvt_pk_bf16_f32 v2, v2, v3
	v_cvt_pk_bf16_f32 v3, v4, v5
	v_cvt_pk_bf16_f32 v4, v6, v7
	v_or_b32_e32 v6, s40, v99
	v_ashrrev_i32_e32 v7, 31, v6
	v_pk_mul_f32 v[8:9], v[36:37], v[12:13]
	v_lshlrev_b64 v[6:7], 13, v[6:7]
	v_cvt_pk_bf16_f32 v5, v8, v9
	v_lshl_add_u64 v[6:7], v[34:35], 0, v[6:7]
	global_store_dwordx4 v[6:7], v[2:5], off
	s_barrier
